# P2 rstd pass: eight 16-byte loads per trip before the wait instead of one load + full wait per trip
# speedup vs baseline: 1.0390x; 1.0145x over previous
.LBB0_279:
	s_mul_hi_i32 s0, s30, 0x92492493
	s_add_i32 s0, s0, s30
	s_lshr_b32 s1, s0, 31
	s_ashr_i32 s0, s0, 3
	s_add_i32 s17, s0, s1
	s_mul_i32 s0, s17, 14
	s_sub_i32 s16, s30, s0
	s_cmp_lt_i32 s16, 6
	s_cselect_b64 s[20:21], -1, 0
	s_cmp_gt_i32 s16, 5
	s_cselect_b64 s[18:19], -1, 0
	s_lshl_b32 s31, s17, 8
	s_and_b64 s[0:1], s[20:21], exec
	s_movk_i32 s0, 0x80
	s_cselect_b32 s33, 0x100, s0
	s_movk_i32 s0, 0x1800
	s_mul_i32 s17, s17, 0x380000
	s_cselect_b32 s1, s0, 0x1a00
	s_mul_hi_i32 s22, s31, 0x3800
	s_add_u32 s17, s6, s17
	s_addc_u32 s23, s7, s22
	s_add_u32 s22, s17, s1
	s_addc_u32 s23, s23, 0
	s_lshr_b32 s1, s33, 1
	s_and_b64 s[20:21], s[20:21], exec
	s_cselect_b32 s17, 7, 6
	v_lshlrev_b32_e32 v2, s17, v65
	v_lshl_add_u64 v[0:1], s[22:23], 0, v[66:67]
	v_lshlrev_b32_e32 v112, 1, v2
	s_mov_b32 s0, 0
	v_lshl_add_u64 v[0:1], v[0:1], 0, v[112:113]
	v_mov_b32_e32 v2, 0
	v_mov_b32_e32 v36, 0
	v_mov_b32_e32 v37, 0
	v_mov_b32_e32 v38, 0
.LBB0_280:
	global_load_dwordx4 v[4:7], v[0:1], off
	global_load_dwordx4 v[8:11], v[0:1], off offset:16
	global_load_dwordx4 v[12:15], v[0:1], off offset:32
	global_load_dwordx4 v[16:19], v[0:1], off offset:48
	global_load_dwordx4 v[20:23], v[0:1], off offset:64
	global_load_dwordx4 v[24:27], v[0:1], off offset:80
	global_load_dwordx4 v[28:31], v[0:1], off offset:96
	global_load_dwordx4 v[32:35], v[0:1], off offset:112
	s_add_i32 s0, s0, 64
	v_lshl_add_u64 v[0:1], v[0:1], 0, 64
	v_lshl_add_u64 v[0:1], v[0:1], 0, 64
	s_cmp_ge_u32 s0, s1
	s_waitcnt vmcnt(7)
	v_lshlrev_b32_e32 v3, 16, v4
	v_and_b32_e32 v4, 0xffff0000, v4
	v_fmac_f32_e32 v2, v3, v3
	v_fmac_f32_e32 v36, v4, v4
	v_lshlrev_b32_e32 v3, 16, v5
	v_and_b32_e32 v5, 0xffff0000, v5
	v_fmac_f32_e32 v37, v3, v3
	v_fmac_f32_e32 v38, v5, v5
	v_lshlrev_b32_e32 v3, 16, v6
	v_and_b32_e32 v6, 0xffff0000, v6
	v_fmac_f32_e32 v2, v3, v3
	v_fmac_f32_e32 v36, v6, v6
	v_lshlrev_b32_e32 v3, 16, v7
	v_and_b32_e32 v7, 0xffff0000, v7
	v_fmac_f32_e32 v37, v3, v3
	v_fmac_f32_e32 v38, v7, v7
	s_waitcnt vmcnt(6)
	v_lshlrev_b32_e32 v3, 16, v8
	v_and_b32_e32 v8, 0xffff0000, v8
	v_fmac_f32_e32 v2, v3, v3
	v_fmac_f32_e32 v36, v8, v8
	v_lshlrev_b32_e32 v3, 16, v9
	v_and_b32_e32 v9, 0xffff0000, v9
	v_fmac_f32_e32 v37, v3, v3
	v_fmac_f32_e32 v38, v9, v9
	v_lshlrev_b32_e32 v3, 16, v10
	v_and_b32_e32 v10, 0xffff0000, v10
	v_fmac_f32_e32 v2, v3, v3
	v_fmac_f32_e32 v36, v10, v10
	v_lshlrev_b32_e32 v3, 16, v11
	v_and_b32_e32 v11, 0xffff0000, v11
	v_fmac_f32_e32 v37, v3, v3
	v_fmac_f32_e32 v38, v11, v11
	s_waitcnt vmcnt(5)
	v_lshlrev_b32_e32 v3, 16, v12
	v_and_b32_e32 v12, 0xffff0000, v12
	v_fmac_f32_e32 v2, v3, v3
	v_fmac_f32_e32 v36, v12, v12
	v_lshlrev_b32_e32 v3, 16, v13
	v_and_b32_e32 v13, 0xffff0000, v13
	v_fmac_f32_e32 v37, v3, v3
	v_fmac_f32_e32 v38, v13, v13
	v_lshlrev_b32_e32 v3, 16, v14
	v_and_b32_e32 v14, 0xffff0000, v14
	v_fmac_f32_e32 v2, v3, v3
	v_fmac_f32_e32 v36, v14, v14
	v_lshlrev_b32_e32 v3, 16, v15
	v_and_b32_e32 v15, 0xffff0000, v15
	v_fmac_f32_e32 v37, v3, v3
	v_fmac_f32_e32 v38, v15, v15
	s_waitcnt vmcnt(4)
	v_lshlrev_b32_e32 v3, 16, v16
	v_and_b32_e32 v16, 0xffff0000, v16
	v_fmac_f32_e32 v2, v3, v3
	v_fmac_f32_e32 v36, v16, v16
	v_lshlrev_b32_e32 v3, 16, v17
	v_and_b32_e32 v17, 0xffff0000, v17
	v_fmac_f32_e32 v37, v3, v3
	v_fmac_f32_e32 v38, v17, v17
	v_lshlrev_b32_e32 v3, 16, v18
	v_and_b32_e32 v18, 0xffff0000, v18
	v_fmac_f32_e32 v2, v3, v3
	v_fmac_f32_e32 v36, v18, v18
	v_lshlrev_b32_e32 v3, 16, v19
	v_and_b32_e32 v19, 0xffff0000, v19
	v_fmac_f32_e32 v37, v3, v3
	v_fmac_f32_e32 v38, v19, v19
	s_waitcnt vmcnt(3)
	v_lshlrev_b32_e32 v3, 16, v20
	v_and_b32_e32 v20, 0xffff0000, v20
	v_fmac_f32_e32 v2, v3, v3
	v_fmac_f32_e32 v36, v20, v20
	v_lshlrev_b32_e32 v3, 16, v21
	v_and_b32_e32 v21, 0xffff0000, v21
	v_fmac_f32_e32 v37, v3, v3
	v_fmac_f32_e32 v38, v21, v21
	v_lshlrev_b32_e32 v3, 16, v22
	v_and_b32_e32 v22, 0xffff0000, v22
	v_fmac_f32_e32 v2, v3, v3
	v_fmac_f32_e32 v36, v22, v22
	v_lshlrev_b32_e32 v3, 16, v23
	v_and_b32_e32 v23, 0xffff0000, v23
	v_fmac_f32_e32 v37, v3, v3
	v_fmac_f32_e32 v38, v23, v23
	s_waitcnt vmcnt(2)
	v_lshlrev_b32_e32 v3, 16, v24
	v_and_b32_e32 v24, 0xffff0000, v24
	v_fmac_f32_e32 v2, v3, v3
	v_fmac_f32_e32 v36, v24, v24
	v_lshlrev_b32_e32 v3, 16, v25
	v_and_b32_e32 v25, 0xffff0000, v25
	v_fmac_f32_e32 v37, v3, v3
	v_fmac_f32_e32 v38, v25, v25
	v_lshlrev_b32_e32 v3, 16, v26
	v_and_b32_e32 v26, 0xffff0000, v26
	v_fmac_f32_e32 v2, v3, v3
	v_fmac_f32_e32 v36, v26, v26
	v_lshlrev_b32_e32 v3, 16, v27
	v_and_b32_e32 v27, 0xffff0000, v27
	v_fmac_f32_e32 v37, v3, v3
	v_fmac_f32_e32 v38, v27, v27
	s_waitcnt vmcnt(1)
	v_lshlrev_b32_e32 v3, 16, v28
	v_and_b32_e32 v28, 0xffff0000, v28
	v_fmac_f32_e32 v2, v3, v3
	v_fmac_f32_e32 v36, v28, v28
	v_lshlrev_b32_e32 v3, 16, v29
	v_and_b32_e32 v29, 0xffff0000, v29
	v_fmac_f32_e32 v37, v3, v3
	v_fmac_f32_e32 v38, v29, v29
	v_lshlrev_b32_e32 v3, 16, v30
	v_and_b32_e32 v30, 0xffff0000, v30
	v_fmac_f32_e32 v2, v3, v3
	v_fmac_f32_e32 v36, v30, v30
	v_lshlrev_b32_e32 v3, 16, v31
	v_and_b32_e32 v31, 0xffff0000, v31
	v_fmac_f32_e32 v37, v3, v3
	v_fmac_f32_e32 v38, v31, v31
	s_waitcnt vmcnt(0)
	v_lshlrev_b32_e32 v3, 16, v32
	v_and_b32_e32 v32, 0xffff0000, v32
	v_fmac_f32_e32 v2, v3, v3
	v_fmac_f32_e32 v36, v32, v32
	v_lshlrev_b32_e32 v3, 16, v33
	v_and_b32_e32 v33, 0xffff0000, v33
	v_fmac_f32_e32 v37, v3, v3
	v_fmac_f32_e32 v38, v33, v33
	v_lshlrev_b32_e32 v3, 16, v34
	v_and_b32_e32 v34, 0xffff0000, v34
	v_fmac_f32_e32 v2, v3, v3
	v_fmac_f32_e32 v36, v34, v34
	v_lshlrev_b32_e32 v3, 16, v35
	v_and_b32_e32 v35, 0xffff0000, v35
	v_fmac_f32_e32 v37, v3, v3
	v_fmac_f32_e32 v38, v35, v35
	s_cbranch_scc0 .LBB0_280
	v_add_f32_e32 v2, v2, v36
	v_add_f32_e32 v37, v37, v38
	v_add_f32_e32 v2, v2, v37
	ds_bpermute_b32 v0, v94, v2
	s_and_saveexec_b64 s[20:21], s[2:3]
	s_cbranch_execz .LBB0_283
	v_cvt_f32_u32_e32 v1, s33
	s_waitcnt lgkmcnt(0)
	v_add_f32_e32 v0, v2, v0
	v_div_scale_f32 v2, s[0:1], v1, v1, v0
	v_rcp_f32_e32 v3, v2
	v_div_scale_f32 v4, vcc, v0, v1, v0
	s_mov_b32 s0, 0xf800000
	v_fma_f32 v5, -v2, v3, 1.0
	v_fmac_f32_e32 v3, v5, v3
	v_mul_f32_e32 v5, v4, v3
	v_fma_f32 v6, -v2, v5, v4
	v_fmac_f32_e32 v5, v6, v3
	v_fma_f32 v2, -v2, v5, v4
	v_div_fmas_f32 v2, v2, v3, v5
	v_div_fixup_f32 v0, v2, v1, v0
	v_add_f32_e32 v0, 0x358637bd, v0
	v_mul_f32_e32 v1, 0x4f800000, v0
	v_cmp_gt_f32_e32 vcc, s0, v0
	s_nop 1
	v_cndmask_b32_e32 v0, v0, v1, vcc
	v_sqrt_f32_e32 v1, v0
	s_nop 0
	v_add_u32_e32 v2, -1, v1
	v_add_u32_e32 v3, 1, v1
	v_fma_f32 v4, -v2, v1, v0
	v_fma_f32 v5, -v3, v1, v0
	v_cmp_ge_f32_e64 s[0:1], 0, v4
	s_nop 1
	v_cndmask_b32_e64 v1, v1, v2, s[0:1]
	v_cmp_lt_f32_e64 s[0:1], 0, v5
	s_nop 1
	v_cndmask_b32_e64 v1, v1, v3, s[0:1]
	v_mul_f32_e32 v2, 0x37800000, v1
	v_cndmask_b32_e32 v1, v1, v2, vcc
	v_cmp_class_f32_e32 vcc, v0, v228
	s_nop 1
	v_cndmask_b32_e32 v0, v1, v0, vcc
	v_div_scale_f32 v1, s[0:1], v0, v0, 1.0
	v_rcp_f32_e32 v2, v1
	s_nop 0
	v_fma_f32 v3, -v1, v2, 1.0
	v_fmac_f32_e32 v2, v3, v2
	v_div_scale_f32 v3, vcc, 1.0, v0, 1.0
	v_mul_f32_e32 v4, v3, v2
	v_fma_f32 v5, -v1, v4, v3
	v_fmac_f32_e32 v4, v5, v2
	v_fma_f32 v1, -v1, v4, v3
	v_div_fmas_f32 v1, v1, v2, v4
	v_div_fixup_f32 v0, v1, v0, 1.0
	ds_write_b32 v95, v0
